# all GEMM1 epilogue stores nt sc1 + no entry grid.sync
# baseline (speedup 1.0000x reference)
; __device__ __forceinline__ unsigned cvt_pk_bf16(float lo, float hi) { f32x2_t v = {lo, hi}; bf16x2_t b = __builtin_convertvector(v, bf16x2_t); return __builtin_bit_cast(unsigned, b); }
; #define EPI_FENCE() asm volatile("" ::: "memory")
; #define EPI_LANE() int t__ = threadIdx.x; asm volatile("" : "+v"(t__)); const int wid__ = __builtin_amdgcn_readfirstlane(t__ >> 6); wr = wid__ >> 2; wc = wid__ & 3; fr = t__ & 15; fq = (t__ & 63) >> 4
;     template <int MODE> __device__ __forceinline__ void run(const f32x4 (&acc)[2][2][4][2], const Unit& u, int wr, int wc, int fr, int fq) const {
;         EPI_LANE();
;         const int pn = u.pn, colt = pn * BM, t = colt >> 9;
;         char* base = (MODE == 2) ? (char*)(O + (size_t)6 * ((size_t)MTOK * 512)) + ((size_t)(((pn - 12) * 128 + u.pm) * 8 + wid__)) * 16384
;                                  : (char*)(O + (size_t)t * ((size_t)MTOK * 512) + (size_t)u.pm * BM * 512 + (colt & 511));
;         unsigned off0 = (MODE == 2) ? (unsigned)((t__ & 63) * 16) : (unsigned)((wr * 64 + fr) * 512 + wc * 32 + 8 * fq) * 2u; asm volatile("" : "+v"(off0));
; #pragma unroll
;         for (int bj = 0; bj < 2; ++bj) {
; #pragma unroll
;             for (int ai = 0; ai < 2; ++ai)
; #pragma unroll
;                 for (int m = 0; m < 4; ++m) { const unsigned off = off0 + ((MODE == 2) ? (unsigned)(((ai * 4 + m) * 2 + bj) * 1024) : (unsigned)((ai * HALF + m * 16) * 512 + bj * HALF) * 2u);
;                     const f32x4 v0 = acc[ai][bj][m][0], v1 = acc[ai][bj][m][1];
;                     u32x4 w; w.x = cvt_pk_bf16(actf<MODE>(v0[0]), actf<MODE>(v0[1])); w.y = cvt_pk_bf16(actf<MODE>(v0[2]), actf<MODE>(v0[3]));
;                     w.z = cvt_pk_bf16(actf<MODE>(v1[0]), actf<MODE>(v1[1])); w.w = cvt_pk_bf16(actf<MODE>(v1[2]), actf<MODE>(v1[3]));
;                     *(u32x4*)(base + off) = w; }
;             EPI_FENCE();
;         }
;     }
.LBB0_411:
	s_and_b32 s55, s72, -2
	s_lshl_b32 s62, s72, 8
	s_cmp_lg_u32 s55, 2
	s_cbranch_scc0 .LBB0_413
	s_ashr_i32 s60, s72, 1
	s_ashr_i32 s61, s60, 31
	s_lshl_b64 s[60:61], s[60:61], 25
	s_add_u32 s73, s90, s60
	s_addc_u32 s74, s91, s61
	s_ashr_i32 s55, s54, 31
	s_lshl_b64 s[60:61], s[54:55], 18
	s_add_u32 s55, s73, s60
	s_addc_u32 s61, s74, s61
	s_and_b32 s60, s62, 0x100
	v_mov_b32_e32 v142, v212
	s_lshl_b32 s60, s60, 1
	s_add_u32 s60, s55, s60
	v_readfirstlane_b32 s63, v142
	s_addc_u32 s61, s61, 0
	s_lshr_b32 s55, s63, 2
	s_and_b32 s55, s55, 0x3fffc0
	v_and_or_b32 v143, v142, 15, s55
	v_lshlrev_b32_e32 v143, 10, v143
	s_and_b32 s55, s63, 0xc0
	v_and_b32_e32 v142, 48, v142
	v_or3_b32 v146, v143, s55, v142
	v_cvt_pk_bf16_f32 v142, v126, v127
	v_cvt_pk_bf16_f32 v143, v128, v129
	v_cvt_pk_bf16_f32 v144, v122, v123
	v_cvt_pk_bf16_f32 v145, v124, v125
	global_store_dwordx4 v146, v[142:145], s[60:61] nt sc1
	v_add_u32_e32 v147, 0x4000, v146
	s_nop 0
	v_cvt_pk_bf16_f32 v142, v118, v119
	v_cvt_pk_bf16_f32 v143, v120, v121
	v_cvt_pk_bf16_f32 v144, v114, v115
	v_cvt_pk_bf16_f32 v145, v116, v117
	global_store_dwordx4 v147, v[142:145], s[60:61] nt sc1
	v_add_u32_e32 v147, 0x8000, v146
	s_nop 0
	v_cvt_pk_bf16_f32 v142, v110, v111
	v_cvt_pk_bf16_f32 v143, v112, v113
	v_cvt_pk_bf16_f32 v144, v106, v107
	v_cvt_pk_bf16_f32 v145, v108, v109
	global_store_dwordx4 v147, v[142:145], s[60:61] nt sc1
	v_add_u32_e32 v147, 0xc000, v146
	s_nop 0
	v_cvt_pk_bf16_f32 v142, v102, v103
	v_cvt_pk_bf16_f32 v143, v104, v105
	v_cvt_pk_bf16_f32 v144, v98, v99
	v_cvt_pk_bf16_f32 v145, v100, v101
	global_store_dwordx4 v147, v[142:145], s[60:61] nt sc1
	v_add_u32_e32 v147, 0x20000, v146
	s_nop 0
	v_cvt_pk_bf16_f32 v142, v92, v93
	v_cvt_pk_bf16_f32 v143, v94, v95
	v_cvt_pk_bf16_f32 v144, v88, v89
	v_cvt_pk_bf16_f32 v145, v90, v91
	global_store_dwordx4 v147, v[142:145], s[60:61] nt sc1
	v_add_u32_e32 v147, 0x24000, v146
	s_nop 0
	v_cvt_pk_bf16_f32 v142, v84, v85
	v_cvt_pk_bf16_f32 v143, v86, v87
	v_cvt_pk_bf16_f32 v144, v80, v81
	v_cvt_pk_bf16_f32 v145, v82, v83
	global_store_dwordx4 v147, v[142:145], s[60:61] nt sc1
	v_add_u32_e32 v147, 0x28000, v146
	s_nop 0
	v_cvt_pk_bf16_f32 v142, v76, v77
	v_cvt_pk_bf16_f32 v143, v78, v79
	v_cvt_pk_bf16_f32 v144, v72, v73
	v_cvt_pk_bf16_f32 v145, v74, v75
	global_store_dwordx4 v147, v[142:145], s[60:61] nt sc1
	v_add_u32_e32 v147, 0x2c000, v146
	s_nop 0
	v_cvt_pk_bf16_f32 v142, v12, v13
	v_cvt_pk_bf16_f32 v143, v14, v15
	v_cvt_pk_bf16_f32 v144, v8, v9
	v_cvt_pk_bf16_f32 v145, v10, v11
	global_store_dwordx4 v147, v[142:145], s[60:61] nt sc1
	v_add_u32_e32 v147, 0x100, v146
	s_nop 0
	v_cvt_pk_bf16_f32 v142, v68, v69
	v_cvt_pk_bf16_f32 v143, v70, v71
	v_cvt_pk_bf16_f32 v144, v64, v65
	v_cvt_pk_bf16_f32 v145, v66, v67
	global_store_dwordx4 v147, v[142:145], s[60:61] nt sc1
	v_add_u32_e32 v147, 0x4100, v146
	s_nop 0
	v_cvt_pk_bf16_f32 v142, v60, v61
	v_cvt_pk_bf16_f32 v143, v62, v63
	v_cvt_pk_bf16_f32 v144, v56, v57
	v_cvt_pk_bf16_f32 v145, v58, v59
	global_store_dwordx4 v147, v[142:145], s[60:61] nt sc1
	v_add_u32_e32 v147, 0x8100, v146
	s_nop 0
	v_cvt_pk_bf16_f32 v142, v52, v53
	v_cvt_pk_bf16_f32 v143, v54, v55
	v_cvt_pk_bf16_f32 v144, v48, v49
	v_cvt_pk_bf16_f32 v145, v50, v51
	global_store_dwordx4 v147, v[142:145], s[60:61] nt sc1
	v_add_u32_e32 v147, 0xc100, v146
	s_nop 0
	v_cvt_pk_bf16_f32 v142, v44, v45
	v_cvt_pk_bf16_f32 v143, v46, v47
	v_cvt_pk_bf16_f32 v144, v40, v41
	v_cvt_pk_bf16_f32 v145, v42, v43
	global_store_dwordx4 v147, v[142:145], s[60:61] nt sc1
	v_add_u32_e32 v147, 0x20100, v146
	s_nop 0
	v_cvt_pk_bf16_f32 v142, v36, v37
	v_cvt_pk_bf16_f32 v143, v38, v39
	v_cvt_pk_bf16_f32 v144, v32, v33
	v_cvt_pk_bf16_f32 v145, v34, v35
	global_store_dwordx4 v147, v[142:145], s[60:61] nt sc1
	v_add_u32_e32 v147, 0x24100, v146
	s_nop 0
	v_cvt_pk_bf16_f32 v142, v28, v29
	v_cvt_pk_bf16_f32 v143, v30, v31
	v_cvt_pk_bf16_f32 v144, v24, v25
	v_cvt_pk_bf16_f32 v145, v26, v27
	global_store_dwordx4 v147, v[142:145], s[60:61] nt sc1
	v_add_u32_e32 v147, 0x28100, v146
	v_add_u32_e32 v146, 0x2c100, v146
	v_cvt_pk_bf16_f32 v142, v20, v21
	v_cvt_pk_bf16_f32 v143, v22, v23
	v_cvt_pk_bf16_f32 v144, v16, v17
	v_cvt_pk_bf16_f32 v145, v18, v19
	global_store_dwordx4 v147, v[142:145], s[60:61] nt sc1
	s_nop 1
	v_cvt_pk_bf16_f32 v142, v4, v5
	v_cvt_pk_bf16_f32 v143, v6, v7
	v_cvt_pk_bf16_f32 v144, v0, v1
	v_cvt_pk_bf16_f32 v145, v2, v3
	global_store_dwordx4 v146, v[142:145], s[60:61] nt sc1
	s_mov_b64 s[60:61], 0
; __device__ __forceinline__ unsigned cvt_pk_bf16(float lo, float hi) { f32x2_t v = {lo, hi}; bf16x2_t b = __builtin_convertvector(v, bf16x2_t); return __builtin_bit_cast(unsigned, b); }
; template <int MODE> __device__ __forceinline__ float actf(float v) {
;     ...
;     if (MODE == 3) return v * QSCALE;
;     template <int MODE> __device__ __forceinline__ void run(const f32x4 (&acc)[2][2][4][2], const Unit& u, int wr, int wc, int fr, int fq) const {
;     ...
;         const int pn = u.pn, colt = pn * BM, t = colt >> 9;
;         char* base = (MODE == 2) ? (char*)(O + (size_t)6 * ((size_t)MTOK * 512)) + ((size_t)(((pn - 12) * 128 + u.pm) * 8 + wid__)) * 16384
;                                  : (char*)(O + (size_t)t * ((size_t)MTOK * 512) + (size_t)u.pm * BM * 512 + (colt & 511));
;         unsigned off0 = (MODE == 2) ? (unsigned)((t__ & 63) * 16) : (unsigned)((wr * 64 + fr) * 512 + wc * 32 + 8 * fq) * 2u; asm volatile("" : "+v"(off0));
; #pragma unroll
;         for (int bj = 0; bj < 2; ++bj) {
; #pragma unroll
;             for (int ai = 0; ai < 2; ++ai)
; #pragma unroll
;                 for (int m = 0; m < 4; ++m) { const unsigned off = off0 + ((MODE == 2) ? (unsigned)(((ai * 4 + m) * 2 + bj) * 1024) : (unsigned)((ai * HALF + m * 16) * 512 + bj * HALF) * 2u);
;                     const f32x4 v0 = acc[ai][bj][m][0], v1 = acc[ai][bj][m][1];
;                     u32x4 w; w.x = cvt_pk_bf16(actf<MODE>(v0[0]), actf<MODE>(v0[1])); w.y = cvt_pk_bf16(actf<MODE>(v0[2]), actf<MODE>(v0[3]));
;                     w.z = cvt_pk_bf16(actf<MODE>(v1[0]), actf<MODE>(v1[1])); w.w = cvt_pk_bf16(actf<MODE>(v1[2]), actf<MODE>(v1[3]));
;                     *(u32x4*)(base + off) = w; }
.LBB0_413:
	s_andn2_b64 vcc, exec, s[60:61]
	s_cbranch_vccnz .LBB0_415
	s_ashr_i32 s55, s54, 31
	s_lshl_b64 s[60:61], s[54:55], 18
	s_add_u32 s55, s89, s60
	s_addc_u32 s61, s3, s61
	s_and_b32 s60, s62, 0x100
	v_mov_b32_e32 v142, v212
	s_lshl_b32 s60, s60, 1
	s_add_u32 s60, s55, s60
	v_readfirstlane_b32 s63, v142
	s_addc_u32 s61, s61, 0
	s_lshr_b32 s55, s63, 2
	s_and_b32 s55, s55, 0x3fffc0
	v_and_or_b32 v143, v142, 15, s55
	v_lshlrev_b32_e32 v143, 10, v143
	s_and_b32 s55, s63, 0xc0
	v_and_b32_e32 v142, 48, v142
	s_mov_b32 s24, 0x3e38aa3b
	v_or3_b32 v148, v143, s55, v142
	v_pk_mul_f32 v[142:143], v[126:127], s[24:25] op_sel_hi:[1,0]
	v_pk_mul_f32 v[144:145], v[128:129], s[24:25] op_sel_hi:[1,0]
	v_cvt_pk_bf16_f32 v142, v142, v143
	v_cvt_pk_bf16_f32 v143, v144, v145
	v_pk_mul_f32 v[144:145], v[122:123], s[24:25] op_sel_hi:[1,0]
	v_pk_mul_f32 v[146:147], v[124:125], s[24:25] op_sel_hi:[1,0]
	v_cvt_pk_bf16_f32 v144, v144, v145
	v_cvt_pk_bf16_f32 v145, v146, v147
	global_store_dwordx4 v148, v[142:145], s[60:61] nt sc1
	v_pk_mul_f32 v[146:147], v[116:117], s[24:25] op_sel_hi:[1,0]
	v_add_u32_e32 v149, 0x4000, v148
	v_pk_mul_f32 v[142:143], v[118:119], s[24:25] op_sel_hi:[1,0]
	v_pk_mul_f32 v[144:145], v[120:121], s[24:25] op_sel_hi:[1,0]
	v_cvt_pk_bf16_f32 v142, v142, v143
	v_cvt_pk_bf16_f32 v143, v144, v145
	v_pk_mul_f32 v[144:145], v[114:115], s[24:25] op_sel_hi:[1,0]
	s_nop 0
	v_cvt_pk_bf16_f32 v144, v144, v145
	v_cvt_pk_bf16_f32 v145, v146, v147
	global_store_dwordx4 v149, v[142:145], s[60:61] nt sc1
	v_pk_mul_f32 v[146:147], v[108:109], s[24:25] op_sel_hi:[1,0]
	v_add_u32_e32 v149, 0x8000, v148
	v_pk_mul_f32 v[142:143], v[110:111], s[24:25] op_sel_hi:[1,0]
	v_pk_mul_f32 v[144:145], v[112:113], s[24:25] op_sel_hi:[1,0]
	v_cvt_pk_bf16_f32 v142, v142, v143
	v_cvt_pk_bf16_f32 v143, v144, v145
	v_pk_mul_f32 v[144:145], v[106:107], s[24:25] op_sel_hi:[1,0]
	s_nop 0
	v_cvt_pk_bf16_f32 v144, v144, v145
	v_cvt_pk_bf16_f32 v145, v146, v147
	global_store_dwordx4 v149, v[142:145], s[60:61] nt sc1
	v_pk_mul_f32 v[146:147], v[100:101], s[24:25] op_sel_hi:[1,0]
	v_add_u32_e32 v149, 0xc000, v148
	v_pk_mul_f32 v[142:143], v[102:103], s[24:25] op_sel_hi:[1,0]
	v_pk_mul_f32 v[144:145], v[104:105], s[24:25] op_sel_hi:[1,0]
	v_cvt_pk_bf16_f32 v142, v142, v143
	v_cvt_pk_bf16_f32 v143, v144, v145
	v_pk_mul_f32 v[144:145], v[98:99], s[24:25] op_sel_hi:[1,0]
	s_nop 0
	v_cvt_pk_bf16_f32 v144, v144, v145
	v_cvt_pk_bf16_f32 v145, v146, v147
	global_store_dwordx4 v149, v[142:145], s[60:61] nt sc1
	v_pk_mul_f32 v[146:147], v[90:91], s[24:25] op_sel_hi:[1,0]
	v_add_u32_e32 v149, 0x20000, v148
	v_pk_mul_f32 v[142:143], v[92:93], s[24:25] op_sel_hi:[1,0]
	v_pk_mul_f32 v[144:145], v[94:95], s[24:25] op_sel_hi:[1,0]
	v_cvt_pk_bf16_f32 v142, v142, v143
	v_cvt_pk_bf16_f32 v143, v144, v145
	v_pk_mul_f32 v[144:145], v[88:89], s[24:25] op_sel_hi:[1,0]
	s_nop 0
	v_cvt_pk_bf16_f32 v144, v144, v145
	v_cvt_pk_bf16_f32 v145, v146, v147
	global_store_dwordx4 v149, v[142:145], s[60:61] nt sc1
	v_pk_mul_f32 v[146:147], v[82:83], s[24:25] op_sel_hi:[1,0]
	v_add_u32_e32 v149, 0x24000, v148
	v_pk_mul_f32 v[142:143], v[84:85], s[24:25] op_sel_hi:[1,0]
	v_pk_mul_f32 v[144:145], v[86:87], s[24:25] op_sel_hi:[1,0]
	v_cvt_pk_bf16_f32 v142, v142, v143
	v_cvt_pk_bf16_f32 v143, v144, v145
	v_pk_mul_f32 v[144:145], v[80:81], s[24:25] op_sel_hi:[1,0]
	s_nop 0
	v_cvt_pk_bf16_f32 v144, v144, v145
	v_cvt_pk_bf16_f32 v145, v146, v147
	global_store_dwordx4 v149, v[142:145], s[60:61] nt sc1
	v_pk_mul_f32 v[146:147], v[74:75], s[24:25] op_sel_hi:[1,0]
	v_add_u32_e32 v149, 0x28000, v148
	v_pk_mul_f32 v[142:143], v[76:77], s[24:25] op_sel_hi:[1,0]
	v_pk_mul_f32 v[144:145], v[78:79], s[24:25] op_sel_hi:[1,0]
	v_cvt_pk_bf16_f32 v142, v142, v143
	v_cvt_pk_bf16_f32 v143, v144, v145
	v_pk_mul_f32 v[144:145], v[72:73], s[24:25] op_sel_hi:[1,0]
	s_nop 0
	v_cvt_pk_bf16_f32 v144, v144, v145
	v_cvt_pk_bf16_f32 v145, v146, v147
	global_store_dwordx4 v149, v[142:145], s[60:61] nt sc1
	v_pk_mul_f32 v[146:147], v[10:11], s[24:25] op_sel_hi:[1,0]
	v_add_u32_e32 v149, 0x2c000, v148
	v_pk_mul_f32 v[142:143], v[12:13], s[24:25] op_sel_hi:[1,0]
	v_pk_mul_f32 v[144:145], v[14:15], s[24:25] op_sel_hi:[1,0]
; __device__ __forceinline__ unsigned cvt_pk_bf16(float lo, float hi) { f32x2_t v = {lo, hi}; bf16x2_t b = __builtin_convertvector(v, bf16x2_t); return __builtin_bit_cast(unsigned, b); }
; template <int MODE> __device__ __forceinline__ float actf(float v) {
;     ...
;     if (MODE == 3) return v * QSCALE;
;     template <int MODE> __device__ __forceinline__ void run(const f32x4 (&acc)[2][2][4][2], const Unit& u, int wr, int wc, int fr, int fq) const {
;     ...
;         const int pn = u.pn, colt = pn * BM, t = colt >> 9;
;         char* base = (MODE == 2) ? (char*)(O + (size_t)6 * ((size_t)MTOK * 512)) + ((size_t)(((pn - 12) * 128 + u.pm) * 8 + wid__)) * 16384
;                                  : (char*)(O + (size_t)t * ((size_t)MTOK * 512) + (size_t)u.pm * BM * 512 + (colt & 511));
;         unsigned off0 = (MODE == 2) ? (unsigned)((t__ & 63) * 16) : (unsigned)((wr * 64 + fr) * 512 + wc * 32 + 8 * fq) * 2u; asm volatile("" : "+v"(off0));
; #pragma unroll
;         for (int bj = 0; bj < 2; ++bj) {
; #pragma unroll
;             for (int ai = 0; ai < 2; ++ai)
; #pragma unroll
;                 for (int m = 0; m < 4; ++m) { const unsigned off = off0 + ((MODE == 2) ? (unsigned)(((ai * 4 + m) * 2 + bj) * 1024) : (unsigned)((ai * HALF + m * 16) * 512 + bj * HALF) * 2u);
;                     const f32x4 v0 = acc[ai][bj][m][0], v1 = acc[ai][bj][m][1];
;                     u32x4 w; w.x = cvt_pk_bf16(actf<MODE>(v0[0]), actf<MODE>(v0[1])); w.y = cvt_pk_bf16(actf<MODE>(v0[2]), actf<MODE>(v0[3]));
;                     w.z = cvt_pk_bf16(actf<MODE>(v1[0]), actf<MODE>(v1[1])); w.w = cvt_pk_bf16(actf<MODE>(v1[2]), actf<MODE>(v1[3]));
;                     *(u32x4*)(base + off) = w; }
	v_cvt_pk_bf16_f32 v142, v142, v143
	v_cvt_pk_bf16_f32 v143, v144, v145
	v_pk_mul_f32 v[144:145], v[8:9], s[24:25] op_sel_hi:[1,0]
	s_nop 0
	v_cvt_pk_bf16_f32 v144, v144, v145
	v_cvt_pk_bf16_f32 v145, v146, v147
	global_store_dwordx4 v149, v[142:145], s[60:61] nt sc1
	v_pk_mul_f32 v[146:147], v[66:67], s[24:25] op_sel_hi:[1,0]
	v_add_u32_e32 v149, 0x100, v148
	v_pk_mul_f32 v[142:143], v[68:69], s[24:25] op_sel_hi:[1,0]
	v_pk_mul_f32 v[144:145], v[70:71], s[24:25] op_sel_hi:[1,0]
	v_cvt_pk_bf16_f32 v142, v142, v143
	v_cvt_pk_bf16_f32 v143, v144, v145
	v_pk_mul_f32 v[144:145], v[64:65], s[24:25] op_sel_hi:[1,0]
	s_nop 0
	v_cvt_pk_bf16_f32 v144, v144, v145
	v_cvt_pk_bf16_f32 v145, v146, v147
	global_store_dwordx4 v149, v[142:145], s[60:61] nt sc1
	v_pk_mul_f32 v[146:147], v[58:59], s[24:25] op_sel_hi:[1,0]
	v_add_u32_e32 v149, 0x4100, v148
	v_pk_mul_f32 v[142:143], v[60:61], s[24:25] op_sel_hi:[1,0]
	v_pk_mul_f32 v[144:145], v[62:63], s[24:25] op_sel_hi:[1,0]
	v_cvt_pk_bf16_f32 v142, v142, v143
	v_cvt_pk_bf16_f32 v143, v144, v145
	v_pk_mul_f32 v[144:145], v[56:57], s[24:25] op_sel_hi:[1,0]
	s_nop 0
	v_cvt_pk_bf16_f32 v144, v144, v145
	v_cvt_pk_bf16_f32 v145, v146, v147
	global_store_dwordx4 v149, v[142:145], s[60:61] nt sc1
	v_pk_mul_f32 v[146:147], v[50:51], s[24:25] op_sel_hi:[1,0]
	v_add_u32_e32 v149, 0x8100, v148
	v_pk_mul_f32 v[142:143], v[52:53], s[24:25] op_sel_hi:[1,0]
	v_pk_mul_f32 v[144:145], v[54:55], s[24:25] op_sel_hi:[1,0]
	v_cvt_pk_bf16_f32 v142, v142, v143
	v_cvt_pk_bf16_f32 v143, v144, v145
	v_pk_mul_f32 v[144:145], v[48:49], s[24:25] op_sel_hi:[1,0]
	s_nop 0
	v_cvt_pk_bf16_f32 v144, v144, v145
	v_cvt_pk_bf16_f32 v145, v146, v147
	global_store_dwordx4 v149, v[142:145], s[60:61] nt sc1
	v_pk_mul_f32 v[146:147], v[42:43], s[24:25] op_sel_hi:[1,0]
	v_add_u32_e32 v149, 0xc100, v148
	v_pk_mul_f32 v[142:143], v[44:45], s[24:25] op_sel_hi:[1,0]
	v_pk_mul_f32 v[144:145], v[46:47], s[24:25] op_sel_hi:[1,0]
	v_cvt_pk_bf16_f32 v142, v142, v143
	v_cvt_pk_bf16_f32 v143, v144, v145
	v_pk_mul_f32 v[144:145], v[40:41], s[24:25] op_sel_hi:[1,0]
	s_nop 0
	v_cvt_pk_bf16_f32 v144, v144, v145
	v_cvt_pk_bf16_f32 v145, v146, v147
	global_store_dwordx4 v149, v[142:145], s[60:61] nt sc1
	v_pk_mul_f32 v[146:147], v[34:35], s[24:25] op_sel_hi:[1,0]
	v_add_u32_e32 v149, 0x20100, v148
	v_pk_mul_f32 v[142:143], v[36:37], s[24:25] op_sel_hi:[1,0]
	v_pk_mul_f32 v[144:145], v[38:39], s[24:25] op_sel_hi:[1,0]
	v_cvt_pk_bf16_f32 v142, v142, v143
	v_cvt_pk_bf16_f32 v143, v144, v145
	v_pk_mul_f32 v[144:145], v[32:33], s[24:25] op_sel_hi:[1,0]
	s_nop 0
	v_cvt_pk_bf16_f32 v144, v144, v145
	v_cvt_pk_bf16_f32 v145, v146, v147
	global_store_dwordx4 v149, v[142:145], s[60:61] nt sc1
	v_pk_mul_f32 v[146:147], v[26:27], s[24:25] op_sel_hi:[1,0]
	v_add_u32_e32 v149, 0x24100, v148
	v_pk_mul_f32 v[142:143], v[28:29], s[24:25] op_sel_hi:[1,0]
	v_pk_mul_f32 v[144:145], v[30:31], s[24:25] op_sel_hi:[1,0]
	v_cvt_pk_bf16_f32 v142, v142, v143
	v_cvt_pk_bf16_f32 v143, v144, v145
	v_pk_mul_f32 v[144:145], v[24:25], s[24:25] op_sel_hi:[1,0]
	s_nop 0
	v_cvt_pk_bf16_f32 v144, v144, v145
	v_cvt_pk_bf16_f32 v145, v146, v147
	global_store_dwordx4 v149, v[142:145], s[60:61] nt sc1
	v_pk_mul_f32 v[146:147], v[18:19], s[24:25] op_sel_hi:[1,0]
	v_add_u32_e32 v149, 0x28100, v148
	v_pk_mul_f32 v[142:143], v[20:21], s[24:25] op_sel_hi:[1,0]
	v_pk_mul_f32 v[144:145], v[22:23], s[24:25] op_sel_hi:[1,0]
	v_cvt_pk_bf16_f32 v142, v142, v143
	v_cvt_pk_bf16_f32 v143, v144, v145
	v_pk_mul_f32 v[144:145], v[16:17], s[24:25] op_sel_hi:[1,0]
	v_add_u32_e32 v148, 0x2c100, v148
	v_cvt_pk_bf16_f32 v144, v144, v145
	v_cvt_pk_bf16_f32 v145, v146, v147
	global_store_dwordx4 v149, v[142:145], s[60:61] nt sc1
	v_pk_mul_f32 v[146:147], v[2:3], s[24:25] op_sel_hi:[1,0]
	s_nop 0
	v_pk_mul_f32 v[142:143], v[4:5], s[24:25] op_sel_hi:[1,0]
	v_pk_mul_f32 v[144:145], v[6:7], s[24:25] op_sel_hi:[1,0]
	v_cvt_pk_bf16_f32 v142, v142, v143
	v_cvt_pk_bf16_f32 v143, v144, v145
	v_pk_mul_f32 v[144:145], v[0:1], s[24:25] op_sel_hi:[1,0]
	s_nop 0
	v_cvt_pk_bf16_f32 v144, v144, v145
	v_cvt_pk_bf16_f32 v145, v146, v147
	global_store_dwordx4 v148, v[142:145], s[60:61] nt sc1
